# v129 + rope loop software-pipelined: next row's two loads issued one iteration ahead (counted vmcnt(2)), removing the per-row exposed load latency
# baseline (speedup 1.0000x reference)
.LBB0_438:
	s_cmp_ge_i32 s66, s64
	s_cbranch_scc1 .LBB0_441
	v_lshlrev_b32_e32 v2, 3, v218
	v_and_b32_e32 v2, 24, v2
	v_cvt_f32_ubyte0_e32 v3, v2
	v_mul_f32_e32 v3, 0xc1135d8e, v3
	v_mul_f32_e32 v3, 0x3d000000, v3
	v_mul_f32_e32 v3, 0x3fb8aa3b, v3
	s_waitcnt vmcnt(0)
	v_exp_f32_e32 v12, v3
	v_or_b32_e32 v3, 1, v2
	v_cvt_f32_ubyte0_e32 v3, v3
	v_mul_f32_e32 v3, 0xc1135d8e, v3
	v_mul_f32_e32 v3, 0x3d000000, v3
	v_mul_f32_e32 v3, 0x3fb8aa3b, v3
	v_exp_f32_e32 v13, v3
	v_or_b32_e32 v3, 2, v2
	v_cvt_f32_ubyte0_e32 v3, v3
	v_mul_f32_e32 v3, 0xc1135d8e, v3
	v_mul_f32_e32 v3, 0x3d000000, v3
	v_mul_f32_e32 v3, 0x3fb8aa3b, v3
	v_exp_f32_e32 v14, v3
	v_or_b32_e32 v3, 3, v2
	v_cvt_f32_ubyte0_e32 v3, v3
	v_mul_f32_e32 v3, 0xc1135d8e, v3
	v_mul_f32_e32 v3, 0x3d000000, v3
	v_mul_f32_e32 v3, 0x3fb8aa3b, v3
	v_exp_f32_e32 v15, v3
	v_or_b32_e32 v3, 4, v2
	v_cvt_f32_ubyte0_e32 v3, v3
	v_mul_f32_e32 v3, 0xc1135d8e, v3
	v_mul_f32_e32 v3, 0x3d000000, v3
	v_mul_f32_e32 v3, 0x3fb8aa3b, v3
	v_exp_f32_e32 v16, v3
	v_or_b32_e32 v3, 5, v2
	v_cvt_f32_ubyte0_e32 v3, v3
	v_mul_f32_e32 v3, 0xc1135d8e, v3
	v_mul_f32_e32 v3, 0x3d000000, v3
	v_mul_f32_e32 v3, 0x3fb8aa3b, v3
	v_exp_f32_e32 v17, v3
	v_or_b32_e32 v3, 6, v2
	v_or_b32_e32 v2, 7, v2
	v_cvt_f32_ubyte0_e32 v2, v2
	v_cvt_f32_ubyte0_e32 v3, v3
	v_mul_f32_e32 v2, 0xc1135d8e, v2
	v_mul_f32_e32 v3, 0xc1135d8e, v3
	v_mul_f32_e32 v2, 0x3d000000, v2
	v_lshrrev_b32_e32 v0, 2, v158
	v_mul_f32_e32 v3, 0x3d000000, v3
	v_mul_f32_e32 v2, 0x3fb8aa3b, v2
	v_mul_u32_u24_e32 v0, 0x140, v0
	v_mul_f32_e32 v3, 0x3fb8aa3b, v3
	v_exp_f32_e32 v19, v2
	s_mul_hi_i32 s3, s66, 0x2800
	s_mul_i32 s4, s66, 0x2800
	v_and_b32_e32 v2, 3, v218
	v_exp_f32_e32 v18, v3
	v_lshl_or_b32 v2, v2, 4, s4
	v_mov_b32_e32 v3, s3
	v_lshlrev_b32_e32 v0, 1, v0
	v_lshl_add_u64 v[2:3], v[2:3], 0, v[0:1]
	v_lshl_add_u64 v[2:3], s[54:55], 0, v[2:3]
	s_mov_b64 s[4:5], 0x11f80200
	v_lshl_add_u64 v[10:11], v[2:3], 0, s[4:5]
	s_mul_hi_i32 s5, s1, 0x2800
	s_mul_i32 s4, s1, 0x2800
	s_mov_b32 s3, s66
	global_load_dwordx4 v[36:39], v[10:11], off
	global_load_dwordx4 v[40:43], v[10:11], off offset:64
	global_load_dword v46, v[10:11], off
	global_load_dword v46, v[10:11], off
.LBB0_440:
	s_add_i32 s6, s92, s3
	s_add_i32 s7, s6, 0xffff8000
	s_lshr_b32 s7, s7, 6
	s_add_i32 s7, s7, 16
	s_ashr_i32 s8, s6, 11
	s_cmp_lt_i32 s6, 0x8000
	s_cselect_b32 s6, 0x7ff, 63
	s_cselect_b32 s7, s8, s7
	s_and_b32 s6, s6, s3
	s_or_b32 s8, s6, 0x800
	s_cmp_gt_i32 s7, 15
	s_cselect_b32 s6, s8, s6
	v_cvt_f32_u32_e32 v0, s6
	s_add_i32 s3, s3, s1
	s_cmp_ge_i32 s3, s64
	v_mul_f32_e32 v20, v12, v0
	v_mul_f32_e32 v21, 0.15915494, v20
	v_floor_f32_e32 v21, v21
	v_fma_f32 v20, v20, 0.15915494, -v21
	v_sin_f32_e32 v23, v20
	v_cos_f32_e32 v22, v20
	v_mov_b32_e32 v26, v23
	v_mov_b32_e32 v27, v22
	s_waitcnt vmcnt(2)
	v_mov_b32_e32 v2, v36
	v_mov_b32_e32 v3, v37
	v_mov_b32_e32 v4, v38
	v_mov_b32_e32 v5, v39
	v_mov_b32_e32 v6, v40
	v_mov_b32_e32 v7, v41
	v_mov_b32_e32 v8, v42
	v_mov_b32_e32 v9, v43
	s_cbranch_scc1 .Lrope_nopf
	v_lshl_add_u64 v[44:45], v[10:11], 0, s[4:5]
	global_load_dwordx4 v[36:39], v[44:45], off
	global_load_dwordx4 v[40:43], v[44:45], off offset:64
.Lrope_nopf:
	v_lshlrev_b32_e32 v24, 16, v2
	v_lshlrev_b32_e32 v25, 16, v6
	v_pk_mul_f32 v[20:21], v[22:23], v[24:25]
	v_pk_mul_f32 v[22:23], v[26:27], v[24:25]
	v_sub_f32_e32 v20, v20, v21
	v_add_f32_e32 v21, v22, v23
	v_mul_f32_e32 v22, v13, v0
	v_mul_f32_e32 v23, 0.15915494, v22
	v_floor_f32_e32 v23, v23
	v_fma_f32 v22, v22, 0.15915494, -v23
	v_sin_f32_e32 v23, v22
	v_cos_f32_e32 v22, v22
	v_and_b32_e32 v25, 0xffff0000, v6
	v_and_b32_e32 v24, 0xffff0000, v2
	v_mul_f32_e32 v20, 0x3dd53b94, v20
	v_pk_mul_f32 v[26:27], v[22:23], v[24:25]
	v_mul_f32_e32 v21, 0x3dd53b94, v21
	v_sub_f32_e32 v2, v26, v27
	v_mov_b32_e32 v26, v23
	v_mov_b32_e32 v27, v22
	v_pk_mul_f32 v[22:23], v[26:27], v[24:25]
	v_lshlrev_b32_e32 v25, 16, v7
	v_add_f32_e32 v6, v22, v23
	v_mul_f32_e32 v22, v14, v0
	v_mul_f32_e32 v23, 0.15915494, v22
	v_floor_f32_e32 v23, v23
	v_fma_f32 v22, v22, 0.15915494, -v23
	v_sin_f32_e32 v23, v22
	v_cos_f32_e32 v22, v22
	v_lshlrev_b32_e32 v24, 16, v3
	v_mul_f32_e32 v2, 0x3dd53b94, v2
	v_mul_f32_e32 v6, 0x3dd53b94, v6
	v_pk_mul_f32 v[26:27], v[22:23], v[24:25]
	v_cvt_pk_bf16_f32 v2, v20, v2
	v_cvt_pk_bf16_f32 v6, v21, v6
	s_nop 0
	v_sub_f32_e32 v26, v26, v27
	v_mul_f32_e32 v28, 0x3dd53b94, v26
	v_mov_b32_e32 v26, v23
	v_mov_b32_e32 v27, v22
	v_pk_mul_f32 v[22:23], v[26:27], v[24:25]
	v_and_b32_e32 v25, 0xffff0000, v7
	v_add_f32_e32 v22, v22, v23
	v_mul_f32_e32 v29, 0x3dd53b94, v22
	v_mul_f32_e32 v22, v15, v0
	v_mul_f32_e32 v23, 0.15915494, v22
	v_floor_f32_e32 v23, v23
	v_fma_f32 v22, v22, 0.15915494, -v23
	v_sin_f32_e32 v23, v22
	v_cos_f32_e32 v22, v22
	v_and_b32_e32 v24, 0xffff0000, v3
	v_pk_mul_f32 v[26:27], v[22:23], v[24:25]
	s_nop 0
	v_sub_f32_e32 v3, v26, v27
	v_mov_b32_e32 v26, v23
	v_mov_b32_e32 v27, v22
	v_pk_mul_f32 v[22:23], v[26:27], v[24:25]
	v_lshlrev_b32_e32 v25, 16, v8
	v_add_f32_e32 v7, v22, v23
	v_mul_f32_e32 v22, v16, v0
	v_mul_f32_e32 v23, 0.15915494, v22
	v_floor_f32_e32 v23, v23
	v_fma_f32 v22, v22, 0.15915494, -v23
	v_sin_f32_e32 v23, v22
	v_cos_f32_e32 v22, v22
	v_lshlrev_b32_e32 v24, 16, v4
	v_mul_f32_e32 v3, 0x3dd53b94, v3
	v_mul_f32_e32 v7, 0x3dd53b94, v7
	v_pk_mul_f32 v[26:27], v[22:23], v[24:25]
	v_cvt_pk_bf16_f32 v3, v28, v3
	v_cvt_pk_bf16_f32 v7, v29, v7
	s_nop 0
	v_sub_f32_e32 v26, v26, v27
	v_mul_f32_e32 v30, 0x3dd53b94, v26
	v_mov_b32_e32 v26, v23
	v_mov_b32_e32 v27, v22
	v_pk_mul_f32 v[22:23], v[26:27], v[24:25]
	v_and_b32_e32 v25, 0xffff0000, v8
	v_add_f32_e32 v22, v22, v23
	v_mul_f32_e32 v31, 0x3dd53b94, v22
	v_mul_f32_e32 v22, v17, v0
	v_mul_f32_e32 v23, 0.15915494, v22
	v_floor_f32_e32 v23, v23
	v_fma_f32 v22, v22, 0.15915494, -v23
	v_sin_f32_e32 v23, v22
	v_cos_f32_e32 v22, v22
	v_and_b32_e32 v24, 0xffff0000, v4
	v_pk_mul_f32 v[26:27], v[22:23], v[24:25]
	s_nop 0
	v_sub_f32_e32 v4, v26, v27
	v_mov_b32_e32 v26, v23
	v_mov_b32_e32 v27, v22
	v_pk_mul_f32 v[22:23], v[26:27], v[24:25]
	v_mul_f32_e32 v32, 0x3dd53b94, v4
	v_add_f32_e32 v4, v22, v23
	v_mul_f32_e32 v33, 0x3dd53b94, v4
	v_mul_f32_e32 v4, v18, v0
	v_mul_f32_e32 v8, 0.15915494, v4
	v_floor_f32_e32 v8, v8
	v_fma_f32 v4, v4, 0.15915494, -v8
	v_sin_f32_e32 v23, v4
	v_cos_f32_e32 v22, v4
	v_lshlrev_b32_e32 v25, 16, v9
	v_lshlrev_b32_e32 v24, 16, v5
	v_mul_f32_e32 v0, v19, v0
	v_pk_mul_f32 v[26:27], v[22:23], v[24:25]
	v_and_b32_e32 v9, 0xffff0000, v9
	v_sub_f32_e32 v4, v26, v27
	v_mov_b32_e32 v26, v23
	v_mov_b32_e32 v27, v22
	v_pk_mul_f32 v[22:23], v[26:27], v[24:25]
	v_mul_f32_e32 v34, 0x3dd53b94, v4
	v_add_f32_e32 v4, v22, v23
	v_mul_f32_e32 v24, 0x3dd53b94, v4
	v_mul_f32_e32 v4, 0.15915494, v0
	v_floor_f32_e32 v4, v4
	v_fma_f32 v0, v0, 0.15915494, -v4
	v_sin_f32_e32 v23, v0
	v_cos_f32_e32 v22, v0
	v_and_b32_e32 v8, 0xffff0000, v5
	v_pk_mul_f32 v[4:5], v[22:23], v[8:9]
	s_nop 0
	v_sub_f32_e32 v0, v4, v5
	v_mov_b32_e32 v4, v23
	v_mov_b32_e32 v5, v22
	v_pk_mul_f32 v[4:5], v[4:5], v[8:9]
	v_mul_f32_e32 v0, 0x3dd53b94, v0
	v_add_f32_e32 v4, v4, v5
	v_mul_f32_e32 v9, 0x3dd53b94, v4
	v_cvt_pk_bf16_f32 v4, v30, v32
	v_cvt_pk_bf16_f32 v5, v34, v0
	v_cvt_pk_bf16_f32 v8, v31, v33
	v_cvt_pk_bf16_f32 v9, v24, v9
	global_store_dwordx4 v[10:11], v[2:5], off
	global_store_dwordx4 v[10:11], v[6:9], off offset:64
	v_lshl_add_u64 v[10:11], v[10:11], 0, s[4:5]
	s_cbranch_scc0 .LBB0_440
